# K-loop code placement matched to the baseline's (mod 64 B) by 60 bytes of unreachable padding
# baseline (speedup 1.0000x reference)
; __global__ void __launch_bounds__(512, 2) fwd_megakernel(Params p) {
;     ...
;     if (ph == 1 || ph == 4 || ph == 5 || ph == 7 || ph == 8) {
;       const int gph = ph == 1 ? 0 : ph == 4 ? 1 : ph == 5 ? 2 : ph == 7 ? 3 : 4;
;       const unsigned ldB = gph == 1 ? 4096u * 2u : gph == 4 ? 5632u * 2u : 2048u * 2u;
;       gemm_phase(p, lds, gph, ldB);
;       if (gph == 0) conv_queue(p, lds, (unsigned*)(ws + WS_CTL) + 4, 7680, 16384);
;       if (gph == 3) conv_queue(p, lds, (unsigned*)(ws + WS_CTL) + 5, 16384, 19200);
;       if (gph == 1 && gridDim.x == 256) { xcd_barrier(xb); merge_split_reduce(p); }
;       if (gph == 3 && gridDim.x == 256) { xcd_barrier(xb); ffn_split_reduce(p); }
.LBB0_246:
	v_readlane_b32 s30, v255, 46
	v_readlane_b32 s31, v255, 47
	s_and_b64 vcc, exec, s[30:31]
	s_cbranch_vccnz .LBB0_251
	s_branch .LBB0_1489
	s_nop 0
	s_nop 0
	s_nop 0
	s_nop 0
	s_nop 0
	s_nop 0
	s_nop 0
	s_nop 0
	s_nop 0
	s_nop 0
	s_nop 0
	s_nop 0
	s_nop 0
	s_nop 0
	s_nop 0
